# v21 + removal of the 96 accumulator-zeroing MFMAs that the peeled first K-iterations (srcC = 0) make dead in three phase prologues
# baseline (speedup 1.0000x reference)
.LBB0_101:
	s_andn2_b64 vcc, exec, s[0:1]
	s_mov_b64 s[0:1], -1
	s_cbranch_vccz .LBB0_199
	v_readlane_b32 s0, v252, 22
	v_mov_b32_e32 v37, v0
	v_readlane_b32 s1, v252, 23
	s_andn2_b64 vcc, exec, s[0:1]
	v_readfirstlane_b32 s0, v37
	s_cbranch_vccnz .LBB0_198
	v_lshlrev_b32_e32 v3, 4, v37
	v_add_u32_e32 v2, 0x2000, v3
	v_ashrrev_i32_e32 v4, 31, v2
	v_lshrrev_b32_e32 v4, 22, v4
	v_add_u32_e32 v4, v2, v4
	v_mov_b32_e32 v26, v27
	v_ashrrev_i32_e32 v36, 10, v4
	v_mov_b32_e32 v28, v27
	v_mov_b32_e32 v29, v27
	v_mov_b64_e32 v[6:7], v[26:27]
	v_mul_i32_i24_e32 v4, 0x400, v36
	v_mov_b64_e32 v[8:9], v[28:29]
	v_sub_u32_e32 v2, v2, v4
	v_lshrrev_b32_e32 v4, 4, v2
	v_bitop3_b32 v2, v4, v2, 32 bitop3:0x6c
	v_ashrrev_i32_e32 v4, 31, v2
	v_lshrrev_b32_e32 v4, 26, v4
	v_add_u32_e32 v4, v2, v4
	v_lshlrev_b32_e32 v5, 3, v36
	v_ashrrev_i32_e32 v26, 6, v4
	s_waitcnt lgkmcnt(0)
	v_and_b32_e32 v5, -16, v5
	v_add_u32_e32 v5, v26, v5
	v_and_b32_e32 v10, 3, v26
	s_mov_b32 s8, 0x1fffe0
	v_lshrrev_b32_e32 v11, 2, v5
	v_lshlrev_b32_e32 v12, 1, v5
	v_and_b32_e32 v4, 0xc0, v4
	v_and_or_b32 v10, v5, s8, v10
	v_and_b32_e32 v11, 4, v11
	v_and_b32_e32 v12, 24, v12
	v_sub_u32_e32 v2, v2, v4
	v_or3_b32 v10, v10, v11, v12
	v_lshlrev_b32_e32 v11, 5, v36
	v_ashrrev_i16_sdwa v2, v225, sext(v2) dst_sel:DWORD dst_unused:UNUSED_PAD src0_sel:DWORD src1_sel:BYTE_0
	v_and_b32_e32 v11, 32, v11
	v_bfe_i32 v38, v2, 0, 16
	v_add_lshl_u32 v2, v11, v38, 1
	v_lshl_add_u32 v160, v10, 11, v2
	v_mad_u64_u32 v[162:163], s[26:27], v5, s7, v[2:3]
	v_bfe_i32 v2, v37, 27, 1
	v_lshrrev_b32_e32 v2, 22, v2
	v_add_u32_e32 v2, v3, v2
	v_and_b32_e32 v2, 0xfffffc00, v2
	v_sub_u32_e32 v2, v3, v2
	v_lshrrev_b32_e32 v3, 4, v2
	v_ashrrev_i32_e32 v4, 31, v37
	v_bitop3_b32 v2, v3, v2, 32 bitop3:0x6c
	v_lshrrev_b32_e32 v4, 26, v4
	v_ashrrev_i32_e32 v3, 31, v2
	v_add_u32_e32 v4, v37, v4
	v_lshrrev_b32_e32 v3, 26, v3
	v_ashrrev_i32_e32 v56, 6, v4
	v_add_u32_e32 v3, v2, v3
	v_lshlrev_b32_e32 v4, 3, v56
	v_ashrrev_i32_e32 v39, 6, v3
	v_and_b32_e32 v4, -16, v4
	v_add_u32_e32 v4, v39, v4
	v_and_b32_e32 v5, 3, v39
	v_lshrrev_b32_e32 v18, 2, v4
	v_lshlrev_b32_e32 v19, 1, v4
	v_and_b32_e32 v3, 0xc0, v3
	v_and_or_b32 v5, v4, s8, v5
	v_and_b32_e32 v18, 4, v18
	v_and_b32_e32 v19, 24, v19
	v_sub_u32_e32 v2, v2, v3
	s_ashr_i32 s1, s0, 6
	v_or3_b32 v5, v5, v18, v19
	v_lshlrev_b32_e32 v18, 5, v56
	v_ashrrev_i16_sdwa v2, v225, sext(v2) dst_sel:DWORD dst_unused:UNUSED_PAD src0_sel:DWORD src1_sel:BYTE_0
	s_lshl_b32 s16, s1, 10
	v_and_b32_e32 v18, 32, v18
	v_bfe_i32 v57, v2, 0, 16
	v_add_lshl_u32 v2, v18, v57, 1
	s_add_i32 s17, s16, 0
	v_lshl_add_u32 v164, v5, 11, v2
	v_mov_b32_e32 v58, 0x7f7f7f7f
	s_add_i32 m0, s17, 0x10000
	v_mad_u64_u32 v[166:167], s[26:27], v4, s7, v[2:3]
	global_load_lds_dwordx4 v164, s[86:87]
	s_add_i32 m0, s17, 0x12000
	v_readlane_b32 s26, v251, 37
	global_load_lds_dwordx4 v160, s[86:87]
	s_add_i32 m0, s17, 0x14000
	v_readlane_b32 s27, v251, 38
	global_load_lds_dwordx4 v164, s[74:75]
	s_add_i32 m0, s17, 0x16000
	s_add_i32 s46, s17, 0x2000
	global_load_lds_dwordx4 v160, s[74:75]
	s_mov_b32 m0, s17
	s_add_i32 s47, s17, 0x4000
	global_load_lds_dwordx4 v166, s[26:27]
	s_mov_b32 m0, s46
	s_add_i32 s8, s17, 0x6000
	global_load_lds_dwordx4 v162, s[26:27]
	v_readlane_b32 s26, v251, 53
	s_mov_b32 m0, s47
	v_readlane_b32 s27, v251, 54
	s_ashr_i32 s11, s0, 8
	s_cmp_eq_u32 s11, 1
	s_mov_b64 s[4:5], s[96:97]
	s_cselect_b64 s[58:59], -1, 0
	global_load_lds_dwordx4 v166, s[26:27]
	s_mov_b32 m0, s8
	s_cmp_lg_u32 s11, 1
	global_load_lds_dwordx4 v162, s[26:27]
	s_cbranch_scc1 .LBB0_105
	s_barrier

.LBB0_199:
	s_andn2_b64 vcc, exec, s[0:1]
	s_cbranch_vccnz .LBB0_100
	v_mov_b32_e32 v26, v27
	v_mov_b32_e32 v28, v27
	v_mov_b32_e32 v29, v27
	v_mov_b64_e32 v[10:11], v[26:27]
	v_mov_b32_e32 v2, v0
	v_mov_b64_e32 v[12:13], v[28:29]
	s_mov_b32 s0, 0x3fffe0
	v_bfe_i32 v4, v2, 27, 1
	v_lshlrev_b32_e32 v6, 4, v2
	v_lshrrev_b32_e32 v4, 22, v4
	v_ashrrev_i32_e32 v3, 31, v2
	v_add_u32_e32 v4, v6, v4
	v_lshrrev_b32_e32 v3, 26, v3
	v_and_b32_e32 v4, 0xfffffc00, v4
	v_add_u32_e32 v3, v2, v3
	v_sub_u32_e32 v4, v6, v4
	v_ashrrev_i32_e32 v3, 6, v3
	v_lshrrev_b32_e32 v5, 4, v4
	v_bitop3_b32 v5, v5, v4, 32 bitop3:0x6c
	v_lshlrev_b32_e32 v4, 3, v3
	v_and_b32_e32 v7, -16, v4
	v_ashrrev_i32_e32 v4, 31, v5
	v_lshrrev_b32_e32 v4, 26, v4
	v_add_u32_e32 v8, v5, v4
	v_ashrrev_i32_e32 v4, 6, v8
	v_and_b32_e32 v8, 0xc0, v8
	v_add_u32_e32 v9, v4, v7
	v_sub_u32_e32 v5, v5, v8
	v_lshlrev_b32_e32 v7, 5, v3
	v_ashrrev_i16_sdwa v5, v225, sext(v5) dst_sel:DWORD dst_unused:UNUSED_PAD src0_sel:DWORD src1_sel:BYTE_0
	s_waitcnt lgkmcnt(0)
	v_lshlrev_b32_e32 v8, 1, v9
	v_lshrrev_b32_e32 v14, 2, v9
	v_and_b32_e32 v15, 3, v4
	v_and_b32_e32 v7, 32, v7
	v_bfe_i32 v5, v5, 0, 16
	v_and_b32_e32 v8, 24, v8
	v_and_b32_e32 v14, 4, v14
	v_and_or_b32 v15, v9, s0, v15
	v_or3_b32 v8, v15, v14, v8
	v_add_lshl_u32 v14, v7, v5, 1
	v_add_u32_e32 v7, 0x2000, v6
	v_ashrrev_i32_e32 v6, 31, v7
	v_lshrrev_b32_e32 v6, 22, v6
	v_add_u32_e32 v6, v7, v6
	v_ashrrev_i32_e32 v6, 10, v6
	v_mul_i32_i24_e32 v15, 0x400, v6
	v_sub_u32_e32 v7, v7, v15
	v_lshrrev_b32_e32 v15, 4, v7
	v_bitop3_b32 v15, v15, v7, 32 bitop3:0x6c
	v_lshlrev_b32_e32 v7, 3, v6
	v_and_b32_e32 v16, -16, v7
	v_ashrrev_i32_e32 v7, 31, v15
	v_lshrrev_b32_e32 v7, 26, v7
	v_add_u32_e32 v17, v15, v7
	v_readfirstlane_b32 s30, v2
	v_ashrrev_i32_e32 v7, 6, v17
	v_and_b32_e32 v17, 0xc0, v17
	s_ashr_i32 s31, s30, 6
	v_add_u32_e32 v16, v7, v16
	v_sub_u32_e32 v15, v15, v17
	v_lshl_add_u32 v158, v8, 10, v14
	v_lshlrev_b32_e32 v8, 5, v6
	v_lshlrev_b32_e32 v17, 1, v16
	v_lshrrev_b32_e32 v18, 2, v16
	v_and_b32_e32 v19, 3, v7
	v_lshl_add_u32 v156, v9, 10, v14
	v_and_b32_e32 v9, 32, v8
	v_ashrrev_i16_sdwa v8, v225, sext(v15) dst_sel:DWORD dst_unused:UNUSED_PAD src0_sel:DWORD src1_sel:BYTE_0
	s_lshl_b32 s8, s31, 10
	v_and_b32_e32 v17, 24, v17
	v_and_b32_e32 v18, 4, v18
	v_and_or_b32 v19, v16, s0, v19
	v_bfe_i32 v8, v8, 0, 16
	s_add_i32 s11, s8, 0
	v_or3_b32 v17, v19, v18, v17
	v_add_lshl_u32 v9, v9, v8, 1
	v_mov_b32_e32 v186, 0x7f7f7f7f
	s_add_i32 m0, s11, 0x10000
	v_lshl_add_u32 v162, v17, 10, v9
	global_load_lds_dwordx4 v158, s[36:37]
	s_add_i32 m0, s11, 0x12000
	s_add_i32 s16, s11, 0x2000
	global_load_lds_dwordx4 v162, s[36:37]
	s_add_i32 m0, s11, 0x14000
	v_lshl_add_u32 v160, v16, 10, v9
	global_load_lds_dwordx4 v158, s[34:35]
	s_add_i32 m0, s11, 0x16000
	s_add_i32 s17, s11, 0x4000
	global_load_lds_dwordx4 v162, s[34:35]
	s_mov_b32 m0, s11
	v_readlane_b32 s0, v252, 20
	global_load_lds_dwordx4 v156, s[70:71]
	s_mov_b32 m0, s16
	v_readlane_b32 s1, v252, 21
	global_load_lds_dwordx4 v160, s[70:71]
	s_mov_b32 m0, s17
	s_add_i32 s22, s11, 0x6000
	s_nop 0
	global_load_lds_dwordx4 v156, s[0:1]
	s_mov_b32 m0, s22
	s_ashr_i32 s38, s30, 8
	global_load_lds_dwordx4 v160, s[0:1]
	s_cmp_eq_u32 s38, 1
	s_cselect_b64 s[0:1], -1, 0
	s_cmp_lg_u32 s38, 1
	s_cbranch_scc1 .LBB0_202
	s_barrier

.LBB0_373:
	s_andn2_b64 vcc, exec, s[0:1]
	s_cbranch_vccnz .LBB0_496
	v_readlane_b32 s0, v252, 14
	v_readlane_b32 s4, v253, 49
	s_add_u32 s60, s0, s46
	v_readlane_b32 s0, v252, 15
	v_readlane_b32 s5, v253, 50
	s_addc_u32 s61, s0, 0
	s_mov_b64 s[0:1], -1
	s_and_b64 vcc, exec, s[4:5]
	s_cbranch_vccz .LBB0_464
	v_mov_b32_e32 v6, v0
	s_mov_b32 s4, 0x3fffe0
	v_ashrrev_i32_e32 v3, 31, v6
	v_lshrrev_b32_e32 v3, 26, v3
	v_add_u32_e32 v3, v6, v3
	v_ashrrev_i32_e32 v7, 6, v3
	v_bfe_i32 v3, v6, 27, 1
	v_lshlrev_b32_e32 v2, 4, v6
	v_lshrrev_b32_e32 v3, 22, v3
	v_add_u32_e32 v3, v2, v3
	v_and_b32_e32 v3, 0xfffffc00, v3
	v_sub_u32_e32 v3, v2, v3
	v_lshrrev_b32_e32 v4, 4, v3
	v_bitop3_b32 v3, v4, v3, 32 bitop3:0x6c
	v_ashrrev_i32_e32 v5, 31, v3
	v_lshrrev_b32_e32 v5, 26, v5
	v_add_u32_e32 v5, v3, v5
	v_lshlrev_b32_e32 v4, 3, v7
	v_ashrrev_i32_e32 v8, 6, v5
	v_and_b32_e32 v5, 0xc0, v5
	v_and_b32_e32 v4, -16, v4
	v_sub_u32_e32 v3, v3, v5
	v_add_u32_e32 v4, v8, v4
	v_lshlrev_b32_e32 v9, 5, v7
	v_ashrrev_i16_sdwa v3, v225, sext(v3) dst_sel:DWORD dst_unused:UNUSED_PAD src0_sel:DWORD src1_sel:BYTE_0
	v_and_b32_e32 v10, 32, v9
	v_bfe_i32 v9, v3, 0, 16
	v_lshlrev_b32_e32 v3, 1, v4
	v_lshrrev_b32_e32 v5, 2, v4
	v_and_b32_e32 v11, 3, v8
	v_and_b32_e32 v3, 24, v3
	v_and_b32_e32 v5, 4, v5
	v_and_or_b32 v11, v4, s4, v11
	v_or3_b32 v3, v11, v5, v3
	v_add_lshl_u32 v5, v10, v9, 1
	v_add_u32_e32 v2, 0x2000, v2
	v_lshl_add_u32 v158, v3, 10, v5
	v_ashrrev_i32_e32 v3, 31, v2
	v_lshrrev_b32_e32 v3, 22, v3
	v_add_u32_e32 v3, v2, v3
	v_ashrrev_i32_e32 v10, 10, v3
	v_mul_i32_i24_e32 v3, 0x400, v10
	v_sub_u32_e32 v2, v2, v3
	v_lshrrev_b32_e32 v3, 4, v2
	v_bitop3_b32 v2, v3, v2, 32 bitop3:0x6c
	v_lshl_add_u32 v156, v4, 10, v5
	v_ashrrev_i32_e32 v4, 31, v2
	v_lshrrev_b32_e32 v4, 26, v4
	v_add_u32_e32 v4, v2, v4
	v_lshlrev_b32_e32 v3, 3, v10
	v_ashrrev_i32_e32 v11, 6, v4
	v_and_b32_e32 v4, 0xc0, v4
	v_and_b32_e32 v3, -16, v3
	v_sub_u32_e32 v2, v2, v4
	v_add_u32_e32 v3, v11, v3
	v_ashrrev_i16_sdwa v2, v225, sext(v2) dst_sel:DWORD dst_unused:UNUSED_PAD src0_sel:DWORD src1_sel:BYTE_0
	v_lshlrev_b32_e32 v5, 5, v10
	v_bfe_i32 v12, v2, 0, 16
	v_lshlrev_b32_e32 v2, 1, v3
	v_lshrrev_b32_e32 v4, 2, v3
	v_and_b32_e32 v13, 3, v11
	v_and_b32_e32 v5, 32, v5
	v_and_b32_e32 v2, 24, v2
	v_and_b32_e32 v4, 4, v4
	v_and_or_b32 v13, v3, s4, v13
	v_or3_b32 v2, v13, v4, v2
	v_add_lshl_u32 v4, v5, v12, 1
	v_mov_b32_e32 v26, v27
	v_lshl_add_u32 v160, v3, 10, v4
	v_lshl_add_u32 v162, v2, 10, v4
	v_mov_b32_e32 v28, v27
	v_mov_b32_e32 v29, v27
	v_mov_b64_e32 v[2:3], v[26:27]
	v_mov_b64_e32 v[4:5], v[28:29]
	v_readfirstlane_b32 s0, v6
	s_ashr_i32 s1, s0, 6
	s_ashr_i32 s27, s0, 8
	s_lshl_b32 s8, s1, 10
	v_readlane_b32 s4, v253, 56
	s_add_u32 s11, s60, s4
	s_addc_u32 s12, s61, 0
	v_readlane_b32 s4, v253, 53
	s_add_u32 s20, s11, s4
	s_addc_u32 s21, s12, 0
	s_add_i32 s11, s8, 0
	v_mov_b32_e32 v187, 0x7f7f7f7f
	s_add_i32 m0, s11, 0x10000
	v_readlane_b32 s4, v253, 57
	v_readlane_b32 s5, v253, 58
	s_mov_b32 s76, s46
	s_nop 0
	s_nop 0
	s_waitcnt lgkmcnt(0)
	s_nop 0
	s_nop 0
	s_nop 0
	s_nop 0
	s_nop 0
	s_nop 0
	s_nop 0
	s_nop 0
	s_nop 0
	s_nop 0
	s_nop 0
	s_nop 0
	s_nop 0
	s_nop 0
	s_nop 0
	s_nop 0
	s_nop 0
	s_nop 0
	s_nop 0
	s_nop 0
	global_load_lds_dwordx4 v158, s[20:21]
	s_add_i32 m0, s11, 0x12000
	s_add_u32 s16, s20, 0x20000
	global_load_lds_dwordx4 v162, s[20:21]
	s_addc_u32 s17, s21, 0
	s_add_i32 m0, s11, 0x14000
	s_add_i32 s22, s11, 0x6000
	global_load_lds_dwordx4 v158, s[16:17]
	s_add_i32 m0, s11, 0x16000
	global_load_lds_dwordx4 v162, s[16:17]
	s_mov_b32 m0, s11
	s_add_i32 s16, s11, 0x2000
	global_load_lds_dwordx4 v156, s[4:5]
	s_mov_b32 m0, s16
	s_add_i32 s17, s11, 0x4000
	global_load_lds_dwordx4 v160, s[4:5]
	v_readlane_b32 s4, v253, 59
	s_mov_b32 m0, s17
	v_readlane_b32 s5, v253, 60
	s_cmp_eq_u32 s27, 1
	s_cselect_b64 s[28:29], -1, 0
	s_cmp_lg_u32 s27, 1
	s_nop 1
	global_load_lds_dwordx4 v156, s[4:5]
	s_mov_b32 m0, s22
	s_nop 0
	global_load_lds_dwordx4 v160, s[4:5]
	s_cbranch_scc1 .LBB0_377
	s_barrier
